# hand-written GEMM epilogues for bf16 / relu2 / tail modes: one 32-bit lane offset advanced by scalar row strides, in-place bf16 packing (address math per 16-byte store drops from ~12 VALU to <1)
# baseline (speedup 1.0000x reference)
;   DI void operator()(const f32x4 (&acc)[2][2][4][2], const pg8::Unit& u, int wr, int wc, int fr, int fq) const {
;     { int t_ = threadIdx.x; asm volatile("" : "+v"(t_)); fr = t_ & 15; fq = (t_ >> 4) & 3; }
;     switch (mode) {
;       case EM_BF16: run<EM_BF16>(acc, u, wr, wc, fr, fq); break;
;       case EM_RELU2: run<EM_RELU2>(acc, u, wr, wc, fr, fq); break;
;       case EM_F32: run<EM_F32>(acc, u, wr, wc, fr, fq); break;
;       case EM_QKV: run<EM_QKV>(acc, u, wr, wc, fr, fq); break;
;       case EM_SPLIT: run<EM_SPLIT>(acc, u, wr, wc, fr, fq); break;
;       case EM_TAIL: run<EM_TAIL>(acc, u, wr, wc, fr, fq); break;
;       default: run<EM_QROPE>(acc, u, wr, wc, fr, fq); break;
;     }
.LBB0_490:
	v_mov_b32_e32 v112, v181
	s_cmp_lt_i32 s71, 3
	v_and_b32_e32 v179, 15, v112
	v_bfe_u32 v178, v112, 4, 2
	s_cmp_eq_u32 s71, 2
	s_cbranch_scc1 .Lepi_relu2
	s_cmp_eq_u32 s71, 0
	s_cbranch_scc1 .Lepi_plain
	s_cmp_eq_u32 s71, 6
	s_cbranch_scc1 .Lepi_plain
	s_cmp_lt_i32 s71, 3
	s_mov_b64 s[20:21], -1
	s_cbranch_scc1 .LBB0_668
	s_mov_b64 s[46:47], 0
	s_cmp_lt_i32 s71, 5
	s_mov_b64 s[48:49], 0
	s_cbranch_scc1 .LBB0_631
	s_cmp_gt_i32 s71, 5
	s_cbranch_scc0 .LBB0_560
	s_cmp_eq_u32 s71, 6
	s_mov_b64 s[48:49], -1
	s_cbranch_scc0 .LBB0_559
	s_lshl_b32 s40, s83, 8
	v_or_b32_e32 v112, s78, v179
	s_cmp_lt_u32 s64, 16
	v_add_u32_e32 v136, s40, v112
	s_cselect_b64 s[24:25], -1, 0
	v_ashrrev_i32_e32 v137, 31, v136
	s_and_b64 vcc, exec, s[24:25]
	s_cbranch_vccz .LBB0_496
	v_mul_lo_u32 v138, s89, v136
	v_mul_lo_u32 v139, s88, v137
	v_mad_u64_u32 v[134:135], s[20:21], s88, v136, 0
	v_add3_u32 v135, v135, v139, v138
	v_cvt_pk_bf16_f32 v130, v126, v127
	v_cvt_pk_bf16_f32 v131, v128, v129
	v_cvt_pk_bf16_f32 v132, v122, v123
	v_cvt_pk_bf16_f32 v133, v124, v125
	v_lshl_add_u64 v[140:141], v[134:135], 1, s[90:91]
	s_mov_b64 s[20:21], 0

; DI u32x4 pack8(f32x4 a, f32x4 b) { u32x4 w; w.x = cvtpk(a.x, a.y); w.y = cvtpk(a.z, a.w); w.z = cvtpk(b.x, b.y); w.w = cvtpk(b.z, b.w); return w; }
;   template <int MODE> DI void store8(int row, int col, f32x4 v0, f32x4 v1, int part) const {
;     if (MODE == EM_QKV || MODE == EM_RELU2 || MODE == EM_F32) { const float r_ = rs[row]; v0 *= r_; v1 *= r_; }
;     if (MODE == EM_TAIL) {
;       if (part >= 16) *(u32x4*)(O2 + ((size_t)(part - 16) * 1024 + (row - NPR)) * 2048 + col) = pack8(v0, v1);
;       else *(u32x4*)(O + (size_t)row * ldc + col) = pack8(v0, v1);
;     } else if (MODE == EM_SPLIT) {
;       bf16* d = (part & 1) ? O2 : O; *(u32x4*)(d + (size_t)row * ldc + col) = pack8(v0, v1);
;       if (part & 2) *(u32x4*)(O2 + (size_t)row * ldc + col) = (u32x4){0u, 0u, 0u, 0u};
;     } else if (MODE == EM_BF16) { *(u32x4*)(O + (size_t)row * ldc + col) = pack8(v0, v1); }
;   template <int MODE> DI void run(const f32x4 (&acc)[2][2][4][2], const pg8::Unit& u, int wr, int wc, int fr, int fq) const {
; #pragma unroll
;     for (int ai = 0; ai < 2; ++ai)
; #pragma unroll
;       for (int m = 0; m < 4; ++m) {
;         const int row = u.pm * 256 + ai * 128 + wr * 64 + m * 16 + fr;
; #pragma unroll
;         for (int bj = 0; bj < 2; ++bj) { store8<MODE>(row, u.pn * 256 + bj * 128 + wc * 32 + 8 * fq, acc[ai][bj][m][0], acc[ai][bj][m][1], u.part);
;           if (MODE == EM_QROPE || MODE == EM_QKV) asm volatile("" ::: "memory"); }
;       }
;   }
.Lepi_plain:
	v_or_b32_e32 v130, s78, v179
	v_lshl_add_u32 v130, s83, 8, v130
	s_lshl_b32 s20, s66, 8
	v_lshl_or_b32 v131, v178, 3, s20
	v_or_b32_e32 v131, s79, v131
	v_mul_lo_u32 v132, v130, s88
	v_add_lshl_u32 v132, v132, v131, 1
	s_lshl_b32 s20, s88, 5
	s_mul_i32 s21, s88, 0xa0
	s_mov_b64 s[98:99], s[90:91]
	s_cmp_eq_u32 s71, 6
	s_cbranch_scc0 .Lepi_plain_bd
	s_cmp_lt_u32 s64, 16
	s_cbranch_scc1 .Lepi_plain_bd
	s_add_i32 s98, s64, -16
	s_lshl_b32 s98, s98, 22
	s_sub_i32 s98, s98, 0x4000000
	s_ashr_i32 s99, s98, 31
	s_add_u32 s98, s92, s98
	s_addc_u32 s99, s93, s99
.Lepi_plain_bd:
	v_cvt_pk_bf16_f32 v126, v126, v127
	v_cvt_pk_bf16_f32 v127, v128, v129
	v_cvt_pk_bf16_f32 v128, v122, v123
	v_cvt_pk_bf16_f32 v129, v124, v125
	global_store_dwordx4 v132, v[126:129], s[98:99]
	v_cvt_pk_bf16_f32 v118, v118, v119
	v_cvt_pk_bf16_f32 v119, v120, v121
	v_cvt_pk_bf16_f32 v120, v114, v115
	v_cvt_pk_bf16_f32 v121, v116, v117
	global_store_dwordx4 v132, v[118:121], s[98:99] offset:256
	v_add_u32_e32 v132, s20, v132
	v_cvt_pk_bf16_f32 v108, v108, v109
	v_cvt_pk_bf16_f32 v109, v110, v111
	v_cvt_pk_bf16_f32 v110, v104, v105
	v_cvt_pk_bf16_f32 v111, v106, v107
	global_store_dwordx4 v132, v[108:111], s[98:99]
	v_cvt_pk_bf16_f32 v100, v100, v101
	v_cvt_pk_bf16_f32 v101, v102, v103
	v_cvt_pk_bf16_f32 v102, v96, v97
	v_cvt_pk_bf16_f32 v103, v98, v99
	global_store_dwordx4 v132, v[100:103], s[98:99] offset:256
	v_add_u32_e32 v132, s20, v132
	v_cvt_pk_bf16_f32 v92, v92, v93
	v_cvt_pk_bf16_f32 v93, v94, v95
	v_cvt_pk_bf16_f32 v94, v88, v89
	v_cvt_pk_bf16_f32 v95, v90, v91
	global_store_dwordx4 v132, v[92:95], s[98:99]
	v_cvt_pk_bf16_f32 v84, v84, v85
	v_cvt_pk_bf16_f32 v85, v86, v87
	v_cvt_pk_bf16_f32 v86, v80, v81
	v_cvt_pk_bf16_f32 v87, v82, v83
	global_store_dwordx4 v132, v[84:87], s[98:99] offset:256
	v_add_u32_e32 v132, s20, v132
	v_cvt_pk_bf16_f32 v76, v76, v77
	v_cvt_pk_bf16_f32 v77, v78, v79
	v_cvt_pk_bf16_f32 v78, v72, v73
	v_cvt_pk_bf16_f32 v79, v74, v75
	global_store_dwordx4 v132, v[76:79], s[98:99]
	v_cvt_pk_bf16_f32 v68, v68, v69
	v_cvt_pk_bf16_f32 v69, v70, v71
	v_cvt_pk_bf16_f32 v70, v64, v65
	v_cvt_pk_bf16_f32 v71, v66, v67
	global_store_dwordx4 v132, v[68:71], s[98:99] offset:256
	v_add_u32_e32 v132, s21, v132
	v_cvt_pk_bf16_f32 v60, v60, v61
	v_cvt_pk_bf16_f32 v61, v62, v63
	v_cvt_pk_bf16_f32 v62, v56, v57
	v_cvt_pk_bf16_f32 v63, v58, v59
	global_store_dwordx4 v132, v[60:63], s[98:99]
	v_cvt_pk_bf16_f32 v52, v52, v53
	v_cvt_pk_bf16_f32 v53, v54, v55
	v_cvt_pk_bf16_f32 v54, v48, v49
	v_cvt_pk_bf16_f32 v55, v50, v51
	global_store_dwordx4 v132, v[52:55], s[98:99] offset:256
	v_add_u32_e32 v132, s20, v132
	v_cvt_pk_bf16_f32 v44, v44, v45
	v_cvt_pk_bf16_f32 v45, v46, v47
	v_cvt_pk_bf16_f32 v46, v40, v41
	v_cvt_pk_bf16_f32 v47, v42, v43
	global_store_dwordx4 v132, v[44:47], s[98:99]
	v_cvt_pk_bf16_f32 v36, v36, v37
	v_cvt_pk_bf16_f32 v37, v38, v39
	v_cvt_pk_bf16_f32 v38, v32, v33
	v_cvt_pk_bf16_f32 v39, v34, v35
	global_store_dwordx4 v132, v[36:39], s[98:99] offset:256
	v_add_u32_e32 v132, s20, v132
	v_cvt_pk_bf16_f32 v28, v28, v29
	v_cvt_pk_bf16_f32 v29, v30, v31
	v_cvt_pk_bf16_f32 v30, v24, v25
	v_cvt_pk_bf16_f32 v31, v26, v27
	global_store_dwordx4 v132, v[28:31], s[98:99]
	v_cvt_pk_bf16_f32 v20, v20, v21
	v_cvt_pk_bf16_f32 v21, v22, v23
	v_cvt_pk_bf16_f32 v22, v16, v17
	v_cvt_pk_bf16_f32 v23, v18, v19
	global_store_dwordx4 v132, v[20:23], s[98:99] offset:256
	v_add_u32_e32 v132, s20, v132
	v_cvt_pk_bf16_f32 v12, v12, v13
	v_cvt_pk_bf16_f32 v13, v14, v15
	v_cvt_pk_bf16_f32 v14, v8, v9
	v_cvt_pk_bf16_f32 v15, v10, v11
	global_store_dwordx4 v132, v[12:15], s[98:99]
	v_cvt_pk_bf16_f32 v4, v4, v5
	v_cvt_pk_bf16_f32 v5, v6, v7
	v_cvt_pk_bf16_f32 v6, v0, v1
	v_cvt_pk_bf16_f32 v7, v2, v3
	global_store_dwordx4 v132, v[4:7], s[98:99] offset:256
	s_nop 1
	s_branch .LBB0_837
.Lepi_relu2:
	v_or_b32_e32 v130, s78, v179
	v_lshl_add_u32 v130, s83, 8, v130
	s_lshl_b32 s20, s66, 8
	v_lshl_or_b32 v131, v178, 3, s20
	v_or_b32_e32 v131, s79, v131
	v_mul_lo_u32 v132, v130, s88
	v_add_lshl_u32 v132, v132, v131, 1
	s_lshl_b32 s20, s88, 5
	s_mul_i32 s21, s88, 0xa0
	s_mov_b64 s[98:99], s[90:91]
	v_lshlrev_b32_e32 v133, 2, v130
	global_load_dword v188, v133, s[96:97]
	global_load_dword v189, v133, s[96:97] offset:64
	global_load_dword v190, v133, s[96:97] offset:128
	global_load_dword v191, v133, s[96:97] offset:192
	global_load_dword v192, v133, s[96:97] offset:512
	global_load_dword v193, v133, s[96:97] offset:576
	global_load_dword v194, v133, s[96:97] offset:640
	global_load_dword v195, v133, s[96:97] offset:704
	s_waitcnt vmcnt(0)
; DI u32x4 pack8(f32x4 a, f32x4 b) { u32x4 w; w.x = cvtpk(a.x, a.y); w.y = cvtpk(a.z, a.w); w.z = cvtpk(b.x, b.y); w.w = cvtpk(b.z, b.w); return w; }
;   template <int MODE> DI void store8(int row, int col, f32x4 v0, f32x4 v1, int part) const {
;     if (MODE == EM_QKV || MODE == EM_RELU2 || MODE == EM_F32) { const float r_ = rs[row]; v0 *= r_; v1 *= r_; }
;     if (MODE == EM_TAIL) {
;       if (part >= 16) *(u32x4*)(O2 + ((size_t)(part - 16) * 1024 + (row - NPR)) * 2048 + col) = pack8(v0, v1);
;       else *(u32x4*)(O + (size_t)row * ldc + col) = pack8(v0, v1);
;     } else if (MODE == EM_SPLIT) {
;       bf16* d = (part & 1) ? O2 : O; *(u32x4*)(d + (size_t)row * ldc + col) = pack8(v0, v1);
;       if (part & 2) *(u32x4*)(O2 + (size_t)row * ldc + col) = (u32x4){0u, 0u, 0u, 0u};
;     } else if (MODE == EM_BF16) { *(u32x4*)(O + (size_t)row * ldc + col) = pack8(v0, v1); }
;     else if (MODE == EM_RELU2) {
;       f32x4 a = __builtin_elementwise_max(v0, (f32x4){0.f, 0.f, 0.f, 0.f}), b = __builtin_elementwise_max(v1, (f32x4){0.f, 0.f, 0.f, 0.f});
;       *(u32x4*)(O + (size_t)row * ldc + col) = pack8(a * a, b * b); }
;   template <int MODE> DI void run(const f32x4 (&acc)[2][2][4][2], const pg8::Unit& u, int wr, int wc, int fr, int fq) const {
; #pragma unroll
;     for (int ai = 0; ai < 2; ++ai)
; #pragma unroll
;       for (int m = 0; m < 4; ++m) {
;         const int row = u.pm * 256 + ai * 128 + wr * 64 + m * 16 + fr;
; #pragma unroll
;         for (int bj = 0; bj < 2; ++bj) { store8<MODE>(row, u.pn * 256 + bj * 128 + wc * 32 + 8 * fq, acc[ai][bj][m][0], acc[ai][bj][m][1], u.part);
;           if (MODE == EM_QROPE || MODE == EM_QKV) asm volatile("" ::: "memory"); }
;       }
;   }
	v_mov_b32_e32 v112, v188
	v_pk_mul_f32 v[126:127], v[126:127], v[112:113] op_sel_hi:[1,0]
	v_pk_mul_f32 v[128:129], v[128:129], v[112:113] op_sel_hi:[1,0]
	v_pk_mul_f32 v[122:123], v[122:123], v[112:113] op_sel_hi:[1,0]
	v_pk_mul_f32 v[124:125], v[124:125], v[112:113] op_sel_hi:[1,0]
	v_max_f32_e32 v126, 0, v126
	v_max_f32_e32 v127, 0, v127
	v_max_f32_e32 v128, 0, v128
	v_max_f32_e32 v129, 0, v129
	v_max_f32_e32 v122, 0, v122
	v_max_f32_e32 v123, 0, v123
	v_max_f32_e32 v124, 0, v124
	v_max_f32_e32 v125, 0, v125
	v_pk_mul_f32 v[126:127], v[126:127], v[126:127]
	v_pk_mul_f32 v[128:129], v[128:129], v[128:129]
	v_pk_mul_f32 v[122:123], v[122:123], v[122:123]
	v_pk_mul_f32 v[124:125], v[124:125], v[124:125]
	v_cvt_pk_bf16_f32 v126, v126, v127
	v_cvt_pk_bf16_f32 v127, v128, v129
	v_cvt_pk_bf16_f32 v128, v122, v123
	v_cvt_pk_bf16_f32 v129, v124, v125
	global_store_dwordx4 v132, v[126:129], s[98:99]
	v_pk_mul_f32 v[118:119], v[118:119], v[112:113] op_sel_hi:[1,0]
	v_pk_mul_f32 v[120:121], v[120:121], v[112:113] op_sel_hi:[1,0]
	v_pk_mul_f32 v[114:115], v[114:115], v[112:113] op_sel_hi:[1,0]
	v_pk_mul_f32 v[116:117], v[116:117], v[112:113] op_sel_hi:[1,0]
	v_max_f32_e32 v118, 0, v118
	v_max_f32_e32 v119, 0, v119
	v_max_f32_e32 v120, 0, v120
	v_max_f32_e32 v121, 0, v121
	v_max_f32_e32 v114, 0, v114
	v_max_f32_e32 v115, 0, v115
	v_max_f32_e32 v116, 0, v116
	v_max_f32_e32 v117, 0, v117
	v_pk_mul_f32 v[118:119], v[118:119], v[118:119]
	v_pk_mul_f32 v[120:121], v[120:121], v[120:121]
	v_pk_mul_f32 v[114:115], v[114:115], v[114:115]
	v_pk_mul_f32 v[116:117], v[116:117], v[116:117]
	v_cvt_pk_bf16_f32 v118, v118, v119
	v_cvt_pk_bf16_f32 v119, v120, v121
	v_cvt_pk_bf16_f32 v120, v114, v115
	v_cvt_pk_bf16_f32 v121, v116, v117
	global_store_dwordx4 v132, v[118:121], s[98:99] offset:256
	v_add_u32_e32 v132, s20, v132
	v_mov_b32_e32 v112, v189
	v_pk_mul_f32 v[108:109], v[108:109], v[112:113] op_sel_hi:[1,0]
	v_pk_mul_f32 v[110:111], v[110:111], v[112:113] op_sel_hi:[1,0]
	v_pk_mul_f32 v[104:105], v[104:105], v[112:113] op_sel_hi:[1,0]
	v_pk_mul_f32 v[106:107], v[106:107], v[112:113] op_sel_hi:[1,0]
	v_max_f32_e32 v108, 0, v108
	v_max_f32_e32 v109, 0, v109
	v_max_f32_e32 v110, 0, v110
	v_max_f32_e32 v111, 0, v111
	v_max_f32_e32 v104, 0, v104
	v_max_f32_e32 v105, 0, v105
	v_max_f32_e32 v106, 0, v106
	v_max_f32_e32 v107, 0, v107
	v_pk_mul_f32 v[108:109], v[108:109], v[108:109]
	v_pk_mul_f32 v[110:111], v[110:111], v[110:111]
	v_pk_mul_f32 v[104:105], v[104:105], v[104:105]
	v_pk_mul_f32 v[106:107], v[106:107], v[106:107]
	v_cvt_pk_bf16_f32 v108, v108, v109
	v_cvt_pk_bf16_f32 v109, v110, v111
	v_cvt_pk_bf16_f32 v110, v104, v105
	v_cvt_pk_bf16_f32 v111, v106, v107
	global_store_dwordx4 v132, v[108:111], s[98:99]
	v_pk_mul_f32 v[100:101], v[100:101], v[112:113] op_sel_hi:[1,0]
	v_pk_mul_f32 v[102:103], v[102:103], v[112:113] op_sel_hi:[1,0]
	v_pk_mul_f32 v[96:97], v[96:97], v[112:113] op_sel_hi:[1,0]
	v_pk_mul_f32 v[98:99], v[98:99], v[112:113] op_sel_hi:[1,0]
	v_max_f32_e32 v100, 0, v100
	v_max_f32_e32 v101, 0, v101
	v_max_f32_e32 v102, 0, v102
	v_max_f32_e32 v103, 0, v103
	v_max_f32_e32 v96, 0, v96
	v_max_f32_e32 v97, 0, v97
	v_max_f32_e32 v98, 0, v98
	v_max_f32_e32 v99, 0, v99
	v_pk_mul_f32 v[100:101], v[100:101], v[100:101]
	v_pk_mul_f32 v[102:103], v[102:103], v[102:103]
	v_pk_mul_f32 v[96:97], v[96:97], v[96:97]
	v_pk_mul_f32 v[98:99], v[98:99], v[98:99]
	v_cvt_pk_bf16_f32 v100, v100, v101
	v_cvt_pk_bf16_f32 v101, v102, v103
	v_cvt_pk_bf16_f32 v102, v96, v97
	v_cvt_pk_bf16_f32 v103, v98, v99
	global_store_dwordx4 v132, v[100:103], s[98:99] offset:256
	v_add_u32_e32 v132, s20, v132
	v_mov_b32_e32 v112, v190
	v_pk_mul_f32 v[92:93], v[92:93], v[112:113] op_sel_hi:[1,0]
	v_pk_mul_f32 v[94:95], v[94:95], v[112:113] op_sel_hi:[1,0]
	v_pk_mul_f32 v[88:89], v[88:89], v[112:113] op_sel_hi:[1,0]
	v_pk_mul_f32 v[90:91], v[90:91], v[112:113] op_sel_hi:[1,0]
	v_max_f32_e32 v92, 0, v92
	v_max_f32_e32 v93, 0, v93
	v_max_f32_e32 v94, 0, v94
	v_max_f32_e32 v95, 0, v95
	v_max_f32_e32 v88, 0, v88
	v_max_f32_e32 v89, 0, v89
	v_max_f32_e32 v90, 0, v90
	v_max_f32_e32 v91, 0, v91
	v_pk_mul_f32 v[92:93], v[92:93], v[92:93]
	v_pk_mul_f32 v[94:95], v[94:95], v[94:95]
	v_pk_mul_f32 v[88:89], v[88:89], v[88:89]
	v_pk_mul_f32 v[90:91], v[90:91], v[90:91]
	v_cvt_pk_bf16_f32 v92, v92, v93
	v_cvt_pk_bf16_f32 v93, v94, v95
	v_cvt_pk_bf16_f32 v94, v88, v89
	v_cvt_pk_bf16_f32 v95, v90, v91
	global_store_dwordx4 v132, v[92:95], s[98:99]
	v_pk_mul_f32 v[84:85], v[84:85], v[112:113] op_sel_hi:[1,0]
	v_pk_mul_f32 v[86:87], v[86:87], v[112:113] op_sel_hi:[1,0]
	v_pk_mul_f32 v[80:81], v[80:81], v[112:113] op_sel_hi:[1,0]
	v_pk_mul_f32 v[82:83], v[82:83], v[112:113] op_sel_hi:[1,0]
	v_max_f32_e32 v84, 0, v84
	v_max_f32_e32 v85, 0, v85
	v_max_f32_e32 v86, 0, v86
	v_max_f32_e32 v87, 0, v87
	v_max_f32_e32 v80, 0, v80
	v_max_f32_e32 v81, 0, v81
	v_max_f32_e32 v82, 0, v82
	v_max_f32_e32 v83, 0, v83
	v_pk_mul_f32 v[84:85], v[84:85], v[84:85]
	v_pk_mul_f32 v[86:87], v[86:87], v[86:87]
	v_pk_mul_f32 v[80:81], v[80:81], v[80:81]
	v_pk_mul_f32 v[82:83], v[82:83], v[82:83]
	v_cvt_pk_bf16_f32 v84, v84, v85
	v_cvt_pk_bf16_f32 v85, v86, v87
	v_cvt_pk_bf16_f32 v86, v80, v81
	v_cvt_pk_bf16_f32 v87, v82, v83
	global_store_dwordx4 v132, v[84:87], s[98:99] offset:256
	v_add_u32_e32 v132, s20, v132
	v_mov_b32_e32 v112, v191
	v_pk_mul_f32 v[76:77], v[76:77], v[112:113] op_sel_hi:[1,0]
	v_pk_mul_f32 v[78:79], v[78:79], v[112:113] op_sel_hi:[1,0]
	v_pk_mul_f32 v[72:73], v[72:73], v[112:113] op_sel_hi:[1,0]
	v_pk_mul_f32 v[74:75], v[74:75], v[112:113] op_sel_hi:[1,0]
	v_max_f32_e32 v76, 0, v76
	v_max_f32_e32 v77, 0, v77
; DI u32x4 pack8(f32x4 a, f32x4 b) { u32x4 w; w.x = cvtpk(a.x, a.y); w.y = cvtpk(a.z, a.w); w.z = cvtpk(b.x, b.y); w.w = cvtpk(b.z, b.w); return w; }
;   template <int MODE> DI void store8(int row, int col, f32x4 v0, f32x4 v1, int part) const {
;     if (MODE == EM_QKV || MODE == EM_RELU2 || MODE == EM_F32) { const float r_ = rs[row]; v0 *= r_; v1 *= r_; }
;     if (MODE == EM_TAIL) {
;       if (part >= 16) *(u32x4*)(O2 + ((size_t)(part - 16) * 1024 + (row - NPR)) * 2048 + col) = pack8(v0, v1);
;       else *(u32x4*)(O + (size_t)row * ldc + col) = pack8(v0, v1);
;     } else if (MODE == EM_SPLIT) {
;       bf16* d = (part & 1) ? O2 : O; *(u32x4*)(d + (size_t)row * ldc + col) = pack8(v0, v1);
;       if (part & 2) *(u32x4*)(O2 + (size_t)row * ldc + col) = (u32x4){0u, 0u, 0u, 0u};
;     } else if (MODE == EM_BF16) { *(u32x4*)(O + (size_t)row * ldc + col) = pack8(v0, v1); }
;     else if (MODE == EM_RELU2) {
;       f32x4 a = __builtin_elementwise_max(v0, (f32x4){0.f, 0.f, 0.f, 0.f}), b = __builtin_elementwise_max(v1, (f32x4){0.f, 0.f, 0.f, 0.f});
;       *(u32x4*)(O + (size_t)row * ldc + col) = pack8(a * a, b * b); }
;   template <int MODE> DI void run(const f32x4 (&acc)[2][2][4][2], const pg8::Unit& u, int wr, int wc, int fr, int fq) const {
; #pragma unroll
;     for (int ai = 0; ai < 2; ++ai)
; #pragma unroll
;       for (int m = 0; m < 4; ++m) {
;         const int row = u.pm * 256 + ai * 128 + wr * 64 + m * 16 + fr;
; #pragma unroll
;         for (int bj = 0; bj < 2; ++bj) { store8<MODE>(row, u.pn * 256 + bj * 128 + wc * 32 + 8 * fq, acc[ai][bj][m][0], acc[ai][bj][m][1], u.part);
;           if (MODE == EM_QROPE || MODE == EM_QKV) asm volatile("" ::: "memory"); }
;       }
;   }
	v_max_f32_e32 v78, 0, v78
	v_max_f32_e32 v79, 0, v79
	v_max_f32_e32 v72, 0, v72
	v_max_f32_e32 v73, 0, v73
	v_max_f32_e32 v74, 0, v74
	v_max_f32_e32 v75, 0, v75
	v_pk_mul_f32 v[76:77], v[76:77], v[76:77]
	v_pk_mul_f32 v[78:79], v[78:79], v[78:79]
	v_pk_mul_f32 v[72:73], v[72:73], v[72:73]
	v_pk_mul_f32 v[74:75], v[74:75], v[74:75]
	v_cvt_pk_bf16_f32 v76, v76, v77
	v_cvt_pk_bf16_f32 v77, v78, v79
	v_cvt_pk_bf16_f32 v78, v72, v73
	v_cvt_pk_bf16_f32 v79, v74, v75
	global_store_dwordx4 v132, v[76:79], s[98:99]
	v_pk_mul_f32 v[68:69], v[68:69], v[112:113] op_sel_hi:[1,0]
	v_pk_mul_f32 v[70:71], v[70:71], v[112:113] op_sel_hi:[1,0]
	v_pk_mul_f32 v[64:65], v[64:65], v[112:113] op_sel_hi:[1,0]
	v_pk_mul_f32 v[66:67], v[66:67], v[112:113] op_sel_hi:[1,0]
	v_max_f32_e32 v68, 0, v68
	v_max_f32_e32 v69, 0, v69
	v_max_f32_e32 v70, 0, v70
	v_max_f32_e32 v71, 0, v71
	v_max_f32_e32 v64, 0, v64
	v_max_f32_e32 v65, 0, v65
	v_max_f32_e32 v66, 0, v66
	v_max_f32_e32 v67, 0, v67
	v_pk_mul_f32 v[68:69], v[68:69], v[68:69]
	v_pk_mul_f32 v[70:71], v[70:71], v[70:71]
	v_pk_mul_f32 v[64:65], v[64:65], v[64:65]
	v_pk_mul_f32 v[66:67], v[66:67], v[66:67]
	v_cvt_pk_bf16_f32 v68, v68, v69
	v_cvt_pk_bf16_f32 v69, v70, v71
	v_cvt_pk_bf16_f32 v70, v64, v65
	v_cvt_pk_bf16_f32 v71, v66, v67
	global_store_dwordx4 v132, v[68:71], s[98:99] offset:256
	v_add_u32_e32 v132, s21, v132
	v_mov_b32_e32 v112, v192
	v_pk_mul_f32 v[60:61], v[60:61], v[112:113] op_sel_hi:[1,0]
	v_pk_mul_f32 v[62:63], v[62:63], v[112:113] op_sel_hi:[1,0]
	v_pk_mul_f32 v[56:57], v[56:57], v[112:113] op_sel_hi:[1,0]
	v_pk_mul_f32 v[58:59], v[58:59], v[112:113] op_sel_hi:[1,0]
	v_max_f32_e32 v60, 0, v60
	v_max_f32_e32 v61, 0, v61
	v_max_f32_e32 v62, 0, v62
	v_max_f32_e32 v63, 0, v63
	v_max_f32_e32 v56, 0, v56
	v_max_f32_e32 v57, 0, v57
	v_max_f32_e32 v58, 0, v58
	v_max_f32_e32 v59, 0, v59
	v_pk_mul_f32 v[60:61], v[60:61], v[60:61]
	v_pk_mul_f32 v[62:63], v[62:63], v[62:63]
	v_pk_mul_f32 v[56:57], v[56:57], v[56:57]
	v_pk_mul_f32 v[58:59], v[58:59], v[58:59]
	v_cvt_pk_bf16_f32 v60, v60, v61
	v_cvt_pk_bf16_f32 v61, v62, v63
	v_cvt_pk_bf16_f32 v62, v56, v57
	v_cvt_pk_bf16_f32 v63, v58, v59
	global_store_dwordx4 v132, v[60:63], s[98:99]
	v_pk_mul_f32 v[52:53], v[52:53], v[112:113] op_sel_hi:[1,0]
	v_pk_mul_f32 v[54:55], v[54:55], v[112:113] op_sel_hi:[1,0]
	v_pk_mul_f32 v[48:49], v[48:49], v[112:113] op_sel_hi:[1,0]
	v_pk_mul_f32 v[50:51], v[50:51], v[112:113] op_sel_hi:[1,0]
	v_max_f32_e32 v52, 0, v52
	v_max_f32_e32 v53, 0, v53
	v_max_f32_e32 v54, 0, v54
	v_max_f32_e32 v55, 0, v55
	v_max_f32_e32 v48, 0, v48
	v_max_f32_e32 v49, 0, v49
	v_max_f32_e32 v50, 0, v50
	v_max_f32_e32 v51, 0, v51
	v_pk_mul_f32 v[52:53], v[52:53], v[52:53]
	v_pk_mul_f32 v[54:55], v[54:55], v[54:55]
	v_pk_mul_f32 v[48:49], v[48:49], v[48:49]
	v_pk_mul_f32 v[50:51], v[50:51], v[50:51]
	v_cvt_pk_bf16_f32 v52, v52, v53
	v_cvt_pk_bf16_f32 v53, v54, v55
	v_cvt_pk_bf16_f32 v54, v48, v49
	v_cvt_pk_bf16_f32 v55, v50, v51
	global_store_dwordx4 v132, v[52:55], s[98:99] offset:256
	v_add_u32_e32 v132, s20, v132
	v_mov_b32_e32 v112, v193
	v_pk_mul_f32 v[44:45], v[44:45], v[112:113] op_sel_hi:[1,0]
	v_pk_mul_f32 v[46:47], v[46:47], v[112:113] op_sel_hi:[1,0]
	v_pk_mul_f32 v[40:41], v[40:41], v[112:113] op_sel_hi:[1,0]
	v_pk_mul_f32 v[42:43], v[42:43], v[112:113] op_sel_hi:[1,0]
	v_max_f32_e32 v44, 0, v44
	v_max_f32_e32 v45, 0, v45
	v_max_f32_e32 v46, 0, v46
	v_max_f32_e32 v47, 0, v47
	v_max_f32_e32 v40, 0, v40
	v_max_f32_e32 v41, 0, v41
	v_max_f32_e32 v42, 0, v42
	v_max_f32_e32 v43, 0, v43
	v_pk_mul_f32 v[44:45], v[44:45], v[44:45]
	v_pk_mul_f32 v[46:47], v[46:47], v[46:47]
	v_pk_mul_f32 v[40:41], v[40:41], v[40:41]
	v_pk_mul_f32 v[42:43], v[42:43], v[42:43]
	v_cvt_pk_bf16_f32 v44, v44, v45
	v_cvt_pk_bf16_f32 v45, v46, v47
	v_cvt_pk_bf16_f32 v46, v40, v41
	v_cvt_pk_bf16_f32 v47, v42, v43
	global_store_dwordx4 v132, v[44:47], s[98:99]
	v_pk_mul_f32 v[36:37], v[36:37], v[112:113] op_sel_hi:[1,0]
	v_pk_mul_f32 v[38:39], v[38:39], v[112:113] op_sel_hi:[1,0]
; DI u32x4 pack8(f32x4 a, f32x4 b) { u32x4 w; w.x = cvtpk(a.x, a.y); w.y = cvtpk(a.z, a.w); w.z = cvtpk(b.x, b.y); w.w = cvtpk(b.z, b.w); return w; }
;   template <int MODE> DI void store8(int row, int col, f32x4 v0, f32x4 v1, int part) const {
;     if (MODE == EM_QKV || MODE == EM_RELU2 || MODE == EM_F32) { const float r_ = rs[row]; v0 *= r_; v1 *= r_; }
;     if (MODE == EM_TAIL) {
;       if (part >= 16) *(u32x4*)(O2 + ((size_t)(part - 16) * 1024 + (row - NPR)) * 2048 + col) = pack8(v0, v1);
;       else *(u32x4*)(O + (size_t)row * ldc + col) = pack8(v0, v1);
;     } else if (MODE == EM_SPLIT) {
;       bf16* d = (part & 1) ? O2 : O; *(u32x4*)(d + (size_t)row * ldc + col) = pack8(v0, v1);
;       if (part & 2) *(u32x4*)(O2 + (size_t)row * ldc + col) = (u32x4){0u, 0u, 0u, 0u};
;     } else if (MODE == EM_BF16) { *(u32x4*)(O + (size_t)row * ldc + col) = pack8(v0, v1); }
;     else if (MODE == EM_RELU2) {
;       f32x4 a = __builtin_elementwise_max(v0, (f32x4){0.f, 0.f, 0.f, 0.f}), b = __builtin_elementwise_max(v1, (f32x4){0.f, 0.f, 0.f, 0.f});
;       *(u32x4*)(O + (size_t)row * ldc + col) = pack8(a * a, b * b); }
	v_pk_mul_f32 v[32:33], v[32:33], v[112:113] op_sel_hi:[1,0]
	v_pk_mul_f32 v[34:35], v[34:35], v[112:113] op_sel_hi:[1,0]
	v_max_f32_e32 v36, 0, v36
	v_max_f32_e32 v37, 0, v37
	v_max_f32_e32 v38, 0, v38
	v_max_f32_e32 v39, 0, v39
	v_max_f32_e32 v32, 0, v32
	v_max_f32_e32 v33, 0, v33
	v_max_f32_e32 v34, 0, v34
	v_max_f32_e32 v35, 0, v35
	v_pk_mul_f32 v[36:37], v[36:37], v[36:37]
	v_pk_mul_f32 v[38:39], v[38:39], v[38:39]
	v_pk_mul_f32 v[32:33], v[32:33], v[32:33]
	v_pk_mul_f32 v[34:35], v[34:35], v[34:35]
	v_cvt_pk_bf16_f32 v36, v36, v37
	v_cvt_pk_bf16_f32 v37, v38, v39
	v_cvt_pk_bf16_f32 v38, v32, v33
	v_cvt_pk_bf16_f32 v39, v34, v35
	global_store_dwordx4 v132, v[36:39], s[98:99] offset:256
	v_add_u32_e32 v132, s20, v132
	v_mov_b32_e32 v112, v194
	v_pk_mul_f32 v[28:29], v[28:29], v[112:113] op_sel_hi:[1,0]
	v_pk_mul_f32 v[30:31], v[30:31], v[112:113] op_sel_hi:[1,0]
	v_pk_mul_f32 v[24:25], v[24:25], v[112:113] op_sel_hi:[1,0]
	v_pk_mul_f32 v[26:27], v[26:27], v[112:113] op_sel_hi:[1,0]
	v_max_f32_e32 v28, 0, v28
	v_max_f32_e32 v29, 0, v29
	v_max_f32_e32 v30, 0, v30
	v_max_f32_e32 v31, 0, v31
	v_max_f32_e32 v24, 0, v24
	v_max_f32_e32 v25, 0, v25
	v_max_f32_e32 v26, 0, v26
	v_max_f32_e32 v27, 0, v27
	v_pk_mul_f32 v[28:29], v[28:29], v[28:29]
	v_pk_mul_f32 v[30:31], v[30:31], v[30:31]
	v_pk_mul_f32 v[24:25], v[24:25], v[24:25]
	v_pk_mul_f32 v[26:27], v[26:27], v[26:27]
	v_cvt_pk_bf16_f32 v28, v28, v29
	v_cvt_pk_bf16_f32 v29, v30, v31
	v_cvt_pk_bf16_f32 v30, v24, v25
	v_cvt_pk_bf16_f32 v31, v26, v27
	global_store_dwordx4 v132, v[28:31], s[98:99]
	v_pk_mul_f32 v[20:21], v[20:21], v[112:113] op_sel_hi:[1,0]
	v_pk_mul_f32 v[22:23], v[22:23], v[112:113] op_sel_hi:[1,0]
	v_pk_mul_f32 v[16:17], v[16:17], v[112:113] op_sel_hi:[1,0]
	v_pk_mul_f32 v[18:19], v[18:19], v[112:113] op_sel_hi:[1,0]
	v_max_f32_e32 v20, 0, v20
	v_max_f32_e32 v21, 0, v21
	v_max_f32_e32 v22, 0, v22
	v_max_f32_e32 v23, 0, v23
	v_max_f32_e32 v16, 0, v16
	v_max_f32_e32 v17, 0, v17
	v_max_f32_e32 v18, 0, v18
	v_max_f32_e32 v19, 0, v19
	v_pk_mul_f32 v[20:21], v[20:21], v[20:21]
	v_pk_mul_f32 v[22:23], v[22:23], v[22:23]
	v_pk_mul_f32 v[16:17], v[16:17], v[16:17]
	v_pk_mul_f32 v[18:19], v[18:19], v[18:19]
	v_cvt_pk_bf16_f32 v20, v20, v21
	v_cvt_pk_bf16_f32 v21, v22, v23
	v_cvt_pk_bf16_f32 v22, v16, v17
	v_cvt_pk_bf16_f32 v23, v18, v19
	global_store_dwordx4 v132, v[20:23], s[98:99] offset:256
	v_add_u32_e32 v132, s20, v132
	v_mov_b32_e32 v112, v195
	v_pk_mul_f32 v[12:13], v[12:13], v[112:113] op_sel_hi:[1,0]
	v_pk_mul_f32 v[14:15], v[14:15], v[112:113] op_sel_hi:[1,0]
	v_pk_mul_f32 v[8:9], v[8:9], v[112:113] op_sel_hi:[1,0]
	v_pk_mul_f32 v[10:11], v[10:11], v[112:113] op_sel_hi:[1,0]
	v_max_f32_e32 v12, 0, v12
	v_max_f32_e32 v13, 0, v13
	v_max_f32_e32 v14, 0, v14
	v_max_f32_e32 v15, 0, v15
	v_max_f32_e32 v8, 0, v8
	v_max_f32_e32 v9, 0, v9
	v_max_f32_e32 v10, 0, v10
	v_max_f32_e32 v11, 0, v11
	v_pk_mul_f32 v[12:13], v[12:13], v[12:13]
	v_pk_mul_f32 v[14:15], v[14:15], v[14:15]
	v_pk_mul_f32 v[8:9], v[8:9], v[8:9]
	v_pk_mul_f32 v[10:11], v[10:11], v[10:11]
	v_cvt_pk_bf16_f32 v12, v12, v13
	v_cvt_pk_bf16_f32 v13, v14, v15
	v_cvt_pk_bf16_f32 v14, v8, v9
	v_cvt_pk_bf16_f32 v15, v10, v11
	global_store_dwordx4 v132, v[12:15], s[98:99]
	v_pk_mul_f32 v[4:5], v[4:5], v[112:113] op_sel_hi:[1,0]
	v_pk_mul_f32 v[6:7], v[6:7], v[112:113] op_sel_hi:[1,0]
	v_pk_mul_f32 v[0:1], v[0:1], v[112:113] op_sel_hi:[1,0]
	v_pk_mul_f32 v[2:3], v[2:3], v[112:113] op_sel_hi:[1,0]
	v_max_f32_e32 v4, 0, v4
	v_max_f32_e32 v5, 0, v5
	v_max_f32_e32 v6, 0, v6
	v_max_f32_e32 v7, 0, v7
	v_max_f32_e32 v0, 0, v0
	v_max_f32_e32 v1, 0, v1
	v_max_f32_e32 v2, 0, v2
	v_max_f32_e32 v3, 0, v3
	v_pk_mul_f32 v[4:5], v[4:5], v[4:5]
	v_pk_mul_f32 v[6:7], v[6:7], v[6:7]
	v_pk_mul_f32 v[0:1], v[0:1], v[0:1]
	v_pk_mul_f32 v[2:3], v[2:3], v[2:3]
	v_cvt_pk_bf16_f32 v4, v4, v5
	v_cvt_pk_bf16_f32 v5, v6, v7
	v_cvt_pk_bf16_f32 v6, v0, v1
	v_cvt_pk_bf16_f32 v7, v2, v3
	global_store_dwordx4 v132, v[4:7], s[98:99] offset:256
	s_nop 1
	s_branch .LBB0_837
